# v13 + removed the redundant post-barrier lgkmcnt(0) at the head of each K-loop MFMA segment
# speedup vs baseline: 1.0100x; 1.0021x over previous
; #define PG8_STAGE(bufoff, gbase, voff) do { _Pragma("unroll") for (int _i = 0; _i < 2; ++_i) \
;         __builtin_amdgcn_global_load_lds((const unsigned*)((const char*)(gbase) + (voff)[_i]), (PG8_LAS unsigned*)(lds + (bufoff) + ldsw + _i * 8192), 16, 0, 0); } while (0)
; #define PG8_LDA(dst, b, h) do { _Pragma("unroll") for (int m = 0; m < 4; ++m) _Pragma("unroll") for (int k = 0; k < 2; ++k) dst[m][k] = *(const PG8_LAS bf16x8*)(lds + PG8_SA(b, h) + aoff + m * 2048 + k * 1024); } while (0)
; #define PG8_LDB(dst, b, h) do { _Pragma("unroll") for (int n = 0; n < 2; ++n) _Pragma("unroll") for (int k = 0; k < 2; ++k) dst[n][k] = *(const PG8_LAS bf16x8*)(lds + PG8_SB(b, h) + boff + n * 2048 + k * 1024); } while (0)
; #define PG8_MMA(ai, bj, At, Bt) do { __builtin_amdgcn_s_setprio(1); _Pragma("unroll") for (int m = 0; m < 4; ++m) _Pragma("unroll") for (int n = 0; n < 2; ++n) _Pragma("unroll") for (int k = 0; k < 2; ++k) \
;         acc[ai][bj][m][n] = __builtin_amdgcn_mfma_f32_16x16x32_bf16(Bt[n][k], At[m][k], acc[ai][bj][m][n], 0, 0, 0); __builtin_amdgcn_s_setprio(0); } while (0)
; #define PG8_WAIT_V(n) asm volatile("s_waitcnt vmcnt(" #n ")" ::: "memory")
; #define PG8_WAIT_L(n) asm volatile("s_waitcnt lgkmcnt(" #n ")" ::: "memory")
; template <class Epi, class Sched, bool ALIGN_EPI = false, bool SP2 = false>
; __device__ __forceinline__ void gemm_phase(PG8_LAS unsigned char* lds, const Gemm g, const Sched& S, const Epi& E) {
;     ...
;             const bool last = (t == nt - 2);
;             const char* a1 = cA + (size_t)(t + 1) * kstep;
;             const char* a2 = last ? nA : cA + (size_t)(t + 2) * kstep; const char* b2 = last ? nB : cB + (size_t)(t + 2) * kstep;
;             const char* a3 = a2 + kstep; const char* b3 = b2 + kstep;
;             if (last && has_next) S.a_ready(nxt);
;             if constexpr (SP2) {
;             PG8_LDB(B0, 0, 0); PG8_LDB(B1, 0, 1); PG8_SCHED; PG8_LDA(At, 0, 0); PG8_STAGE(PG8_SA(1, 1), a1 + hstep, voffA);
;             PG8_WAIT_V(8); PG8_WAIT_L(0); PG8_BAR; PG8_MMA(0, 0, At, B0); PG8_MMA(0, 1, At, B1); PG8_BAR; PG8_SCHED;
;             PG8_LDA(At, 0, 1); PG8_STAGE(PG8_SB(0, 0), b2, voffB); PG8_STAGE(PG8_SB(0, 1), b2 + hstep, voffB); PG8_STAGE(PG8_SA(0, 0), a2, voffA);
;             PG8_WAIT_V(8); PG8_WAIT_L(0); PG8_BAR; PG8_MMA(1, 0, At, B0); PG8_MMA(1, 1, At, B1); PG8_BAR; PG8_SCHED;
.LBB0_33:
	s_add_i32 s1, s0, 2
	s_add_u32 s2, s10, 0x80
	s_addc_u32 s3, s11, 0
	s_add_i32 s33, 0, 0x10000
	s_cmp_eq_u32 s94, s0
	s_cselect_b32 s39, s35, s3
	s_cselect_b32 s38, s34, s2
	v_add_u32_e32 v80, s33, v225
	s_cselect_b32 s3, s37, vcc_hi
	s_cselect_b32 s2, s36, vcc_lo
	s_add_i32 s0, 0, 0x14000
	ds_read_b128 v[130:133], v80
	ds_read_b128 v[134:137], v80 offset:1024
	ds_read_b128 v[154:157], v80 offset:2048
	ds_read_b128 v[158:161], v80 offset:3072
	v_add_u32_e32 v80, s0, v225
	ds_read_b128 v[162:165], v80
	ds_read_b128 v[166:169], v80 offset:1024
	ds_read_b128 v[170:173], v80 offset:2048
	ds_read_b128 v[180:183], v80 offset:3072
	v_lshl_add_u64 v[174:175], s[10:11], 0, v[152:153]
	s_add_i32 m0, s84, 0xc000
	ds_read_b128 v[184:187], v227
	ds_read_b128 v[188:191], v227 offset:1024
	ds_read_b128 v[192:195], v227 offset:2048
	ds_read_b128 v[196:199], v227 offset:3072
	ds_read_b128 v[200:203], v227 offset:4096
	ds_read_b128 v[204:207], v227 offset:5120
	ds_read_b128 v[228:231], v227 offset:6144
	ds_read_b128 v[232:235], v227 offset:7168
	global_load_lds_dwordx4 v[174:175], off
	v_lshl_add_u64 v[174:175], s[10:11], 0, v[150:151]
	s_add_i32 m0, s84, 0xe000
	s_nop 0
	global_load_lds_dwordx4 v[174:175], off
	s_waitcnt vmcnt(8)
	s_waitcnt lgkmcnt(0)
	s_barrier
	s_setprio 1
	v_mfma_f32_16x16x32_bf16 v[126:129], v[130:133], v[184:187], v[126:129]
	v_mfma_f32_16x16x32_bf16 v[118:121], v[154:157], v[184:187], v[118:121]
	v_mfma_f32_16x16x32_bf16 v[110:113], v[130:133], v[192:195], v[110:113]
	v_mfma_f32_16x16x32_bf16 v[102:105], v[154:157], v[192:195], v[102:105]
	v_mfma_f32_16x16x32_bf16 v[94:97], v[130:133], v[200:203], v[94:97]
	v_mfma_f32_16x16x32_bf16 v[86:89], v[154:157], v[200:203], v[86:89]
	v_mfma_f32_16x16x32_bf16 v[76:79], v[130:133], v[228:231], v[76:79]
	v_mfma_f32_16x16x32_bf16 v[68:71], v[154:157], v[228:231], v[68:71]
	v_mfma_f32_16x16x32_bf16 v[126:129], v[134:137], v[188:191], v[126:129]
	v_mfma_f32_16x16x32_bf16 v[118:121], v[158:161], v[188:191], v[118:121]
	v_mfma_f32_16x16x32_bf16 v[110:113], v[134:137], v[196:199], v[110:113]
	v_mfma_f32_16x16x32_bf16 v[102:105], v[158:161], v[196:199], v[102:105]
	v_mfma_f32_16x16x32_bf16 v[94:97], v[134:137], v[204:207], v[94:97]
	v_mfma_f32_16x16x32_bf16 v[86:89], v[158:161], v[204:207], v[86:89]
	v_mfma_f32_16x16x32_bf16 v[76:79], v[134:137], v[232:235], v[76:79]
	v_mfma_f32_16x16x32_bf16 v[68:71], v[158:161], v[232:235], v[68:71]
	s_setprio 0
	s_setprio 1
	v_mfma_f32_16x16x32_bf16 v[122:125], v[162:165], v[184:187], v[122:125]
	v_mfma_f32_16x16x32_bf16 v[114:117], v[170:173], v[184:187], v[114:117]
	v_mfma_f32_16x16x32_bf16 v[106:109], v[162:165], v[192:195], v[106:109]
	v_mfma_f32_16x16x32_bf16 v[98:101], v[170:173], v[192:195], v[98:101]
	v_mfma_f32_16x16x32_bf16 v[90:93], v[162:165], v[200:203], v[90:93]
	v_mfma_f32_16x16x32_bf16 v[82:85], v[170:173], v[200:203], v[82:85]
	v_mfma_f32_16x16x32_bf16 v[72:75], v[162:165], v[228:231], v[72:75]
	v_mfma_f32_16x16x32_bf16 v[64:67], v[170:173], v[228:231], v[64:67]
	v_mfma_f32_16x16x32_bf16 v[122:125], v[166:169], v[188:191], v[122:125]
	v_mfma_f32_16x16x32_bf16 v[114:117], v[180:183], v[188:191], v[114:117]
	v_mfma_f32_16x16x32_bf16 v[106:109], v[166:169], v[196:199], v[106:109]
	v_mfma_f32_16x16x32_bf16 v[98:101], v[180:183], v[196:199], v[98:101]
	v_mfma_f32_16x16x32_bf16 v[90:93], v[166:169], v[204:207], v[90:93]
	v_mfma_f32_16x16x32_bf16 v[82:85], v[180:183], v[204:207], v[82:85]
	v_mfma_f32_16x16x32_bf16 v[72:75], v[166:169], v[232:235], v[72:75]
	v_mfma_f32_16x16x32_bf16 v[64:67], v[180:183], v[232:235], v[64:67]
	s_setprio 0
	s_barrier
	s_add_i32 s33, s33, s83
	v_lshl_add_u64 v[174:175], s[2:3], 0, v[140:141]
	s_mov_b32 m0, s33
	ds_read_b128 v[184:187], v227 offset:16384
	ds_read_b128 v[188:191], v227 offset:17408
	ds_read_b128 v[192:195], v227 offset:18432
	ds_read_b128 v[196:199], v227 offset:19456
	ds_read_b128 v[200:203], v227 offset:20480
	ds_read_b128 v[204:207], v227 offset:21504
	ds_read_b128 v[228:231], v227 offset:22528
	ds_read_b128 v[232:235], v227 offset:23552
	global_load_lds_dwordx4 v[174:175], off
	s_add_i32 m0, s33, 0x2000
	v_lshl_add_u64 v[208:209], s[2:3], 0, v[144:145]
	s_add_u32 s2, s2, s22
	s_addc_u32 s3, s3, 0
	s_add_i32 s0, s0, s83
	global_load_lds_dwordx4 v[208:209], off
	v_lshl_add_u64 v[236:237], s[2:3], 0, v[140:141]
	s_mov_b32 m0, s0
	v_lshl_add_u64 v[238:239], s[2:3], 0, v[144:145]
	global_load_lds_dwordx4 v[236:237], off
	s_add_i32 m0, s0, 0x2000
	v_lshl_add_u64 v[240:241], s[38:39], 0, v[138:139]
	global_load_lds_dwordx4 v[238:239], off
	s_mov_b32 m0, s84
	v_lshl_add_u64 v[242:243], s[38:39], 0, v[142:143]
	global_load_lds_dwordx4 v[240:241], off
	s_mov_b32 m0, s85
	s_nop 0
	global_load_lds_dwordx4 v[242:243], off
	s_waitcnt vmcnt(8)
	s_waitcnt lgkmcnt(0)
	s_barrier
; #define PG8_STAGE(bufoff, gbase, voff) do { _Pragma("unroll") for (int _i = 0; _i < 2; ++_i) \
;         __builtin_amdgcn_global_load_lds((const unsigned*)((const char*)(gbase) + (voff)[_i]), (PG8_LAS unsigned*)(lds + (bufoff) + ldsw + _i * 8192), 16, 0, 0); } while (0)
; #define PG8_LDA(dst, b, h) do { _Pragma("unroll") for (int m = 0; m < 4; ++m) _Pragma("unroll") for (int k = 0; k < 2; ++k) dst[m][k] = *(const PG8_LAS bf16x8*)(lds + PG8_SA(b, h) + aoff + m * 2048 + k * 1024); } while (0)
; #define PG8_LDB(dst, b, h) do { _Pragma("unroll") for (int n = 0; n < 2; ++n) _Pragma("unroll") for (int k = 0; k < 2; ++k) dst[n][k] = *(const PG8_LAS bf16x8*)(lds + PG8_SB(b, h) + boff + n * 2048 + k * 1024); } while (0)
; #define PG8_MMA(ai, bj, At, Bt) do { __builtin_amdgcn_s_setprio(1); _Pragma("unroll") for (int m = 0; m < 4; ++m) _Pragma("unroll") for (int n = 0; n < 2; ++n) _Pragma("unroll") for (int k = 0; k < 2; ++k) \
;         acc[ai][bj][m][n] = __builtin_amdgcn_mfma_f32_16x16x32_bf16(Bt[n][k], At[m][k], acc[ai][bj][m][n], 0, 0, 0); __builtin_amdgcn_s_setprio(0); } while (0)
; #define PG8_WAIT_V(n) asm volatile("s_waitcnt vmcnt(" #n ")" ::: "memory")
; #define PG8_WAIT_L(n) asm volatile("s_waitcnt lgkmcnt(" #n ")" ::: "memory")
; #define PG8_BAR __builtin_amdgcn_s_barrier()
; #define PG8_SCHED __builtin_amdgcn_sched_barrier(0)
; template <class Epi, class Sched, bool ALIGN_EPI = false, bool SP2 = false>
; __device__ __forceinline__ void gemm_phase(PG8_LAS unsigned char* lds, const Gemm g, const Sched& S, const Epi& E) {
;     ...
;             PG8_WAIT_V(8); PG8_WAIT_L(0); PG8_BAR; PG8_MMA(1, 0, At, B0); PG8_MMA(1, 1, At, B1); PG8_BAR; PG8_SCHED;
;             PG8_LDB(B0, 1, 0); PG8_LDB(B1, 1, 1); PG8_SCHED; PG8_LDA(At, 1, 0); PG8_STAGE(PG8_SA(0, 1), a2 + hstep, voffA);
;             PG8_WAIT_V(8); PG8_WAIT_L(0); PG8_BAR; PG8_MMA(0, 0, At, B0); PG8_MMA(0, 1, At, B1); PG8_BAR; PG8_SCHED;
;             PG8_LDA(At, 1, 1); PG8_STAGE(PG8_SB(1, 0), b3, voffB); PG8_STAGE(PG8_SB(1, 1), b3 + hstep, voffB); PG8_STAGE(PG8_SA(1, 0), a3, voffA);
	s_setprio 1
	v_mfma_f32_16x16x32_bf16 v[60:63], v[130:133], v[184:187], v[60:63]
	v_mfma_f32_16x16x32_bf16 v[52:55], v[154:157], v[184:187], v[52:55]
	v_mfma_f32_16x16x32_bf16 v[44:47], v[130:133], v[192:195], v[44:47]
	v_mfma_f32_16x16x32_bf16 v[36:39], v[154:157], v[192:195], v[36:39]
	v_mfma_f32_16x16x32_bf16 v[28:31], v[130:133], v[200:203], v[28:31]
	v_mfma_f32_16x16x32_bf16 v[20:23], v[154:157], v[200:203], v[20:23]
	v_mfma_f32_16x16x32_bf16 v[12:15], v[130:133], v[228:231], v[12:15]
	v_mfma_f32_16x16x32_bf16 v[4:7], v[154:157], v[228:231], v[4:7]
	v_mfma_f32_16x16x32_bf16 v[60:63], v[134:137], v[188:191], v[60:63]
	v_mfma_f32_16x16x32_bf16 v[52:55], v[158:161], v[188:191], v[52:55]
	v_mfma_f32_16x16x32_bf16 v[44:47], v[134:137], v[196:199], v[44:47]
	v_mfma_f32_16x16x32_bf16 v[36:39], v[158:161], v[196:199], v[36:39]
	v_mfma_f32_16x16x32_bf16 v[28:31], v[134:137], v[204:207], v[28:31]
	v_mfma_f32_16x16x32_bf16 v[20:23], v[158:161], v[204:207], v[20:23]
	v_mfma_f32_16x16x32_bf16 v[12:15], v[134:137], v[232:235], v[12:15]
	v_mfma_f32_16x16x32_bf16 v[4:7], v[158:161], v[232:235], v[4:7]
	s_setprio 0
	s_setprio 1
	v_mfma_f32_16x16x32_bf16 v[56:59], v[162:165], v[184:187], v[56:59]
	v_mfma_f32_16x16x32_bf16 v[48:51], v[170:173], v[184:187], v[48:51]
	v_mfma_f32_16x16x32_bf16 v[40:43], v[162:165], v[192:195], v[40:43]
	v_mfma_f32_16x16x32_bf16 v[32:35], v[170:173], v[192:195], v[32:35]
	v_mfma_f32_16x16x32_bf16 v[24:27], v[162:165], v[200:203], v[24:27]
	v_mfma_f32_16x16x32_bf16 v[16:19], v[170:173], v[200:203], v[16:19]
	v_mfma_f32_16x16x32_bf16 v[8:11], v[162:165], v[228:231], v[8:11]
	v_mfma_f32_16x16x32_bf16 v[0:3], v[170:173], v[228:231], v[0:3]
	v_mfma_f32_16x16x32_bf16 v[56:59], v[166:169], v[188:191], v[56:59]
	v_mfma_f32_16x16x32_bf16 v[48:51], v[180:183], v[188:191], v[48:51]
	v_mfma_f32_16x16x32_bf16 v[40:43], v[166:169], v[196:199], v[40:43]
	v_mfma_f32_16x16x32_bf16 v[32:35], v[180:183], v[196:199], v[32:35]
	v_mfma_f32_16x16x32_bf16 v[24:27], v[166:169], v[204:207], v[24:27]
	v_mfma_f32_16x16x32_bf16 v[16:19], v[180:183], v[204:207], v[16:19]
	v_mfma_f32_16x16x32_bf16 v[8:11], v[166:169], v[232:235], v[8:11]
	v_mfma_f32_16x16x32_bf16 v[0:3], v[180:183], v[232:235], v[0:3]
	s_setprio 0
	s_barrier
	s_add_i32 s0, 0, 0x18000
	v_add_u32_e32 v80, s0, v225
	s_add_i32 s33, 0, 0x1c000
	ds_read_b128 v[130:133], v80
	ds_read_b128 v[134:137], v80 offset:1024
	ds_read_b128 v[154:157], v80 offset:2048
	ds_read_b128 v[158:161], v80 offset:3072
	v_add_u32_e32 v80, s33, v225
	ds_read_b128 v[162:165], v80
	ds_read_b128 v[166:169], v80 offset:1024
	ds_read_b128 v[170:173], v80 offset:2048
	ds_read_b128 v[180:183], v80 offset:3072
	s_add_u32 s2, s38, s22
	s_addc_u32 s3, s39, 0
	s_mov_b32 m0, s86
	v_lshl_add_u64 v[244:245], s[2:3], 0, v[138:139]
	ds_read_b128 v[184:187], v227 offset:32768
	ds_read_b128 v[188:191], v227 offset:33792
	ds_read_b128 v[192:195], v227 offset:34816
	ds_read_b128 v[196:199], v227 offset:35840
	ds_read_b128 v[200:203], v227 offset:36864
	ds_read_b128 v[204:207], v227 offset:37888
	ds_read_b128 v[228:231], v227 offset:38912
	ds_read_b128 v[232:235], v227 offset:39936
	global_load_lds_dwordx4 v[244:245], off
	v_lshl_add_u64 v[244:245], s[2:3], 0, v[142:143]
	s_mov_b32 m0, s87
	s_nop 0
	global_load_lds_dwordx4 v[244:245], off
	s_waitcnt vmcnt(8)
	s_waitcnt lgkmcnt(0)
	s_barrier
	s_setprio 1
	v_mfma_f32_16x16x32_bf16 v[126:129], v[130:133], v[184:187], v[126:129]
	v_mfma_f32_16x16x32_bf16 v[118:121], v[154:157], v[184:187], v[118:121]
	v_mfma_f32_16x16x32_bf16 v[110:113], v[130:133], v[192:195], v[110:113]
	v_mfma_f32_16x16x32_bf16 v[102:105], v[154:157], v[192:195], v[102:105]
	v_mfma_f32_16x16x32_bf16 v[94:97], v[130:133], v[200:203], v[94:97]
	v_mfma_f32_16x16x32_bf16 v[86:89], v[154:157], v[200:203], v[86:89]
	v_mfma_f32_16x16x32_bf16 v[76:79], v[130:133], v[228:231], v[76:79]
	v_mfma_f32_16x16x32_bf16 v[68:71], v[154:157], v[228:231], v[68:71]
	v_mfma_f32_16x16x32_bf16 v[126:129], v[134:137], v[188:191], v[126:129]
	v_mfma_f32_16x16x32_bf16 v[118:121], v[158:161], v[188:191], v[118:121]
	v_mfma_f32_16x16x32_bf16 v[110:113], v[134:137], v[196:199], v[110:113]
	v_mfma_f32_16x16x32_bf16 v[102:105], v[158:161], v[196:199], v[102:105]
	v_mfma_f32_16x16x32_bf16 v[94:97], v[134:137], v[204:207], v[94:97]
	v_mfma_f32_16x16x32_bf16 v[86:89], v[158:161], v[204:207], v[86:89]
	v_mfma_f32_16x16x32_bf16 v[76:79], v[134:137], v[232:235], v[76:79]
	v_mfma_f32_16x16x32_bf16 v[68:71], v[158:161], v[232:235], v[68:71]
	s_setprio 0
	s_setprio 1
	v_mfma_f32_16x16x32_bf16 v[122:125], v[162:165], v[184:187], v[122:125]
	v_mfma_f32_16x16x32_bf16 v[114:117], v[170:173], v[184:187], v[114:117]
	v_mfma_f32_16x16x32_bf16 v[106:109], v[162:165], v[192:195], v[106:109]
	v_mfma_f32_16x16x32_bf16 v[98:101], v[170:173], v[192:195], v[98:101]
	v_mfma_f32_16x16x32_bf16 v[90:93], v[162:165], v[200:203], v[90:93]
	v_mfma_f32_16x16x32_bf16 v[82:85], v[170:173], v[200:203], v[82:85]
	v_mfma_f32_16x16x32_bf16 v[72:75], v[162:165], v[228:231], v[72:75]
	v_mfma_f32_16x16x32_bf16 v[64:67], v[170:173], v[228:231], v[64:67]
	v_mfma_f32_16x16x32_bf16 v[122:125], v[166:169], v[188:191], v[122:125]
	v_mfma_f32_16x16x32_bf16 v[114:117], v[180:183], v[188:191], v[114:117]
	v_mfma_f32_16x16x32_bf16 v[106:109], v[166:169], v[196:199], v[106:109]
	v_mfma_f32_16x16x32_bf16 v[98:101], v[180:183], v[196:199], v[98:101]
	v_mfma_f32_16x16x32_bf16 v[90:93], v[166:169], v[204:207], v[90:93]
	v_mfma_f32_16x16x32_bf16 v[82:85], v[180:183], v[204:207], v[82:85]
	v_mfma_f32_16x16x32_bf16 v[72:75], v[166:169], v[232:235], v[72:75]
	v_mfma_f32_16x16x32_bf16 v[64:67], v[180:183], v[232:235], v[64:67]
	s_setprio 0
	s_barrier
; #define PG8_STAGE(bufoff, gbase, voff) do { _Pragma("unroll") for (int _i = 0; _i < 2; ++_i) \
;         __builtin_amdgcn_global_load_lds((const unsigned*)((const char*)(gbase) + (voff)[_i]), (PG8_LAS unsigned*)(lds + (bufoff) + ldsw + _i * 8192), 16, 0, 0); } while (0)
; #define PG8_LDA(dst, b, h) do { _Pragma("unroll") for (int m = 0; m < 4; ++m) _Pragma("unroll") for (int k = 0; k < 2; ++k) dst[m][k] = *(const PG8_LAS bf16x8*)(lds + PG8_SA(b, h) + aoff + m * 2048 + k * 1024); } while (0)
; #define PG8_MMA(ai, bj, At, Bt) do { __builtin_amdgcn_s_setprio(1); _Pragma("unroll") for (int m = 0; m < 4; ++m) _Pragma("unroll") for (int n = 0; n < 2; ++n) _Pragma("unroll") for (int k = 0; k < 2; ++k) \
;         acc[ai][bj][m][n] = __builtin_amdgcn_mfma_f32_16x16x32_bf16(Bt[n][k], At[m][k], acc[ai][bj][m][n], 0, 0, 0); __builtin_amdgcn_s_setprio(0); } while (0)
; #define PG8_WAIT_V(n) asm volatile("s_waitcnt vmcnt(" #n ")" ::: "memory")
; #define PG8_WAIT_L(n) asm volatile("s_waitcnt lgkmcnt(" #n ")" ::: "memory")
; #define PG8_BAR __builtin_amdgcn_s_barrier()
; #define PG8_SCHED __builtin_amdgcn_sched_barrier(0)
; template <class Epi, class Sched, bool ALIGN_EPI = false, bool SP2 = false>
; __device__ __forceinline__ void gemm_phase(PG8_LAS unsigned char* lds, const Gemm g, const Sched& S, const Epi& E) {
;     ...
;             PG8_LDA(At, 1, 1); PG8_STAGE(PG8_SB(1, 0), b3, voffB); PG8_STAGE(PG8_SB(1, 1), b3 + hstep, voffB); PG8_STAGE(PG8_SA(1, 0), a3, voffA);
;             PG8_WAIT_V(8); PG8_WAIT_L(0); PG8_BAR; PG8_MMA(1, 0, At, B0); PG8_MMA(1, 1, At, B1); PG8_BAR; PG8_SCHED;
	s_add_i32 s0, s0, s83
	v_lshl_add_u64 v[174:175], v[174:175], 0, s[66:67]
	s_mov_b32 m0, s0
	ds_read_b128 v[184:187], v227 offset:49152
	ds_read_b128 v[188:191], v227 offset:50176
	ds_read_b128 v[192:195], v227 offset:51200
	ds_read_b128 v[196:199], v227 offset:52224
	ds_read_b128 v[200:203], v227 offset:53248
	ds_read_b128 v[204:207], v227 offset:54272
	ds_read_b128 v[228:231], v227 offset:55296
	ds_read_b128 v[232:235], v227 offset:56320
	global_load_lds_dwordx4 v[174:175], off
	v_lshl_add_u64 v[174:175], v[208:209], 0, s[66:67]
	s_add_i32 m0, s0, 0x2000
	s_add_i32 s0, s33, s83
	global_load_lds_dwordx4 v[174:175], off
	v_lshl_add_u64 v[174:175], v[236:237], 0, s[66:67]
	s_mov_b32 m0, s0
	s_nop 0
	global_load_lds_dwordx4 v[174:175], off
	v_lshl_add_u64 v[174:175], v[238:239], 0, s[66:67]
	s_add_i32 m0, s0, 0x2000
	s_nop 0
	global_load_lds_dwordx4 v[174:175], off
	v_lshl_add_u64 v[174:175], v[240:241], 0, s[66:67]
	s_mov_b32 m0, s65
	s_nop 0
	global_load_lds_dwordx4 v[174:175], off
	v_lshl_add_u64 v[174:175], v[242:243], 0, s[66:67]
	s_mov_b32 m0, s53
	s_nop 0
	global_load_lds_dwordx4 v[174:175], off
	s_waitcnt vmcnt(8)
	s_waitcnt lgkmcnt(0)
	s_barrier
	s_setprio 1
	v_mfma_f32_16x16x32_bf16 v[60:63], v[130:133], v[184:187], v[60:63]
	v_mfma_f32_16x16x32_bf16 v[52:55], v[154:157], v[184:187], v[52:55]
	v_mfma_f32_16x16x32_bf16 v[44:47], v[130:133], v[192:195], v[44:47]
	v_mfma_f32_16x16x32_bf16 v[36:39], v[154:157], v[192:195], v[36:39]
	v_mfma_f32_16x16x32_bf16 v[28:31], v[130:133], v[200:203], v[28:31]
	v_mfma_f32_16x16x32_bf16 v[20:23], v[154:157], v[200:203], v[20:23]
	v_mfma_f32_16x16x32_bf16 v[12:15], v[130:133], v[228:231], v[12:15]
	v_mfma_f32_16x16x32_bf16 v[4:7], v[154:157], v[228:231], v[4:7]
	v_mfma_f32_16x16x32_bf16 v[60:63], v[134:137], v[188:191], v[60:63]
	v_mfma_f32_16x16x32_bf16 v[52:55], v[158:161], v[188:191], v[52:55]
	v_mfma_f32_16x16x32_bf16 v[44:47], v[134:137], v[196:199], v[44:47]
	v_mfma_f32_16x16x32_bf16 v[36:39], v[158:161], v[196:199], v[36:39]
	v_mfma_f32_16x16x32_bf16 v[28:31], v[134:137], v[204:207], v[28:31]
	v_mfma_f32_16x16x32_bf16 v[20:23], v[158:161], v[204:207], v[20:23]
	v_mfma_f32_16x16x32_bf16 v[12:15], v[134:137], v[232:235], v[12:15]
	v_mfma_f32_16x16x32_bf16 v[4:7], v[158:161], v[232:235], v[4:7]
	s_setprio 0
	s_setprio 1
	v_mfma_f32_16x16x32_bf16 v[56:59], v[162:165], v[184:187], v[56:59]
	v_mfma_f32_16x16x32_bf16 v[48:51], v[170:173], v[184:187], v[48:51]
	v_mfma_f32_16x16x32_bf16 v[40:43], v[162:165], v[192:195], v[40:43]
	v_mfma_f32_16x16x32_bf16 v[32:35], v[170:173], v[192:195], v[32:35]
	v_mfma_f32_16x16x32_bf16 v[24:27], v[162:165], v[200:203], v[24:27]
	v_mfma_f32_16x16x32_bf16 v[16:19], v[170:173], v[200:203], v[16:19]
	v_mfma_f32_16x16x32_bf16 v[8:11], v[162:165], v[228:231], v[8:11]
	v_mfma_f32_16x16x32_bf16 v[0:3], v[170:173], v[228:231], v[0:3]
	v_mfma_f32_16x16x32_bf16 v[56:59], v[166:169], v[188:191], v[56:59]
	v_mfma_f32_16x16x32_bf16 v[48:51], v[180:183], v[188:191], v[48:51]
	v_mfma_f32_16x16x32_bf16 v[40:43], v[166:169], v[196:199], v[40:43]
	v_mfma_f32_16x16x32_bf16 v[32:35], v[180:183], v[196:199], v[32:35]
	v_mfma_f32_16x16x32_bf16 v[24:27], v[166:169], v[204:207], v[24:27]
	v_mfma_f32_16x16x32_bf16 v[16:19], v[180:183], v[204:207], v[16:19]
	v_mfma_f32_16x16x32_bf16 v[8:11], v[166:169], v[232:235], v[8:11]
	v_mfma_f32_16x16x32_bf16 v[0:3], v[180:183], v[232:235], v[0:3]
	s_setprio 0
	s_barrier
	s_add_u32 vcc_lo, vcc_lo, 0x100
	s_addc_u32 vcc_hi, vcc_hi, 0
	s_add_u32 s10, s10, 0x100
	s_addc_u32 s11, s11, 0
	s_cmp_ge_u32 s1, s97
	s_mov_b32 s0, s1
	s_cbranch_scc0 .LBB0_33
	s_and_b64 vcc, exec, s[28:29]
	s_cbranch_vccnz .LBB0_37
	v_lshl_add_u32 v154, s54, 8, v147
	s_cmp_lt_i32 s77, 1
	s_mov_b64 s[10:11], -1
	s_cbranch_scc0 .LBB0_38
